# baseline (speedup 1.0000x reference)
; __global__ void __launch_bounds__(512, 2) hymba_fwd(Params p) {
;     ...
;     if (C.G == 0x7fffffff) grid.sync();
.LBB0_227:
	s_nop 0
	global_load_dword v2, v0, s[2:3] offset:32 sc1
	s_waitcnt vmcnt(0)
	v_and_b32_e32 v2, 0xffff0000, v2
	v_cmp_ne_u32_e32 vcc, v2, v1
	s_or_b64 s[4:5], vcc, s[4:5]
	s_andn2_b64 exec, exec, s[4:5]
	s_cbranch_execnz .LBB0_227

; __device__ __forceinline__ unsigned xb_ld(unsigned* p)              { return __hip_atomic_load(p, __ATOMIC_RELAXED, __HIP_MEMORY_SCOPE_AGENT); }
; __device__ __forceinline__ void xcd_barrier_complete(unsigned* bar, unsigned x, unsigned& nloc, unsigned& nx) {
;     ...
;     for (;;) {
;         sum = 0u; cnt = 0u; mine = 0u;
; #pragma unroll
;         for (unsigned j = 0; j < 16; ++j) { const unsigned c = xb_ld(&bar[XB_XCNT(j)]); sum += c; cnt += (c > 0u) ? 1u : 0u; mine = (j == x) ? c : mine; }
;         if (sum == G) break;
;         __builtin_amdgcn_s_sleep(1);
;         if ((++sp & 255u) == 0u) { if (xb_ld(&bar[XB_TMO])) break; if (sp > XB_SPIN_CAP) { atomicAdd(&bar[XB_TMO], 1u); break; } }
;     }
.LBB0_234:
	global_load_dword v15, v16, s[2:3] sc1
	s_waitcnt lgkmcnt(0)
	global_load_dword v0, v16, s[4:5] sc1
	global_load_dword v1, v16, s[8:9] sc1
	global_load_dword v2, v16, s[16:17] sc1
	global_load_dword v3, v16, s[22:23] sc1
	global_load_dword v4, v16, s[24:25] sc1
	global_load_dword v5, v16, s[26:27] sc1
	global_load_dword v6, v16, s[28:29] sc1
	global_load_dword v7, v16, s[30:31] sc1
	global_load_dword v8, v16, s[36:37] sc1
	global_load_dword v9, v16, s[38:39] sc1
	global_load_dword v10, v16, s[44:45] sc1
	global_load_dword v11, v16, s[48:49] sc1
	global_load_dword v12, v16, s[50:51] sc1
	global_load_dword v13, v16, s[52:53] sc1
	global_load_dword v14, v16, s[54:55] sc1
	s_mov_b64 s[60:61], -1
	s_mov_b64 s[62:63], -1
	s_waitcnt vmcnt(14)
	v_add_u32_e32 v17, v0, v15
	s_waitcnt vmcnt(13)
	v_add_u32_e32 v17, v17, v1
	s_waitcnt vmcnt(12)
	v_add_u32_e32 v17, v17, v2
	s_waitcnt vmcnt(11)
	v_add_u32_e32 v17, v17, v3
	s_waitcnt vmcnt(10)
	v_add_u32_e32 v17, v17, v4
	s_waitcnt vmcnt(9)
	v_add_u32_e32 v17, v17, v5
	s_waitcnt vmcnt(8)
	v_add_u32_e32 v17, v17, v6
	s_waitcnt vmcnt(7)
	v_add_u32_e32 v17, v17, v7
	s_waitcnt vmcnt(6)
	v_add_u32_e32 v17, v17, v8
	s_waitcnt vmcnt(5)
	v_add_u32_e32 v17, v17, v9
	s_waitcnt vmcnt(4)
	v_add_u32_e32 v17, v17, v10
	s_waitcnt vmcnt(3)
	v_add_u32_e32 v17, v17, v11
	s_waitcnt vmcnt(2)
	v_add_u32_e32 v17, v17, v12
	s_waitcnt vmcnt(1)
	v_add_u32_e32 v17, v17, v13
	s_waitcnt vmcnt(0)
	v_add_u32_e32 v17, v17, v14
	v_cmp_eq_u32_e32 vcc, s7, v17
	s_cbranch_vccnz .LBB0_233
	s_and_b32 s60, s35, 0xff
	s_cmp_eq_u32 s60, 0
	s_mov_b64 s[60:61], -1
	s_mov_b64 s[64:65], -1
	s_nop 0
	s_cbranch_scc0 .LBB0_238
	global_load_dword v17, v16, s[46:47] sc1
	s_waitcnt vmcnt(0)
	v_cmp_eq_u32_e32 vcc, 0, v17
	s_cbranch_vccnz .LBB0_240
	s_mov_b64 s[64:65], 0

; __device__ __forceinline__ unsigned xb_ld(unsigned* p)              { return __hip_atomic_load(p, __ATOMIC_RELAXED, __HIP_MEMORY_SCOPE_AGENT); }
; __device__ __forceinline__ unsigned xb_add(unsigned* p, unsigned v) { return __hip_atomic_fetch_add(p, v, __ATOMIC_RELAXED, __HIP_MEMORY_SCOPE_AGENT); }
; #define XB_SPIN(cond, bar) do { unsigned _sp = 0; while (cond) { __builtin_amdgcn_s_sleep(1); \
;     if ((++_sp & 255u) == 0u) { if (xb_ld(&(bar)[XB_TMO])) break; if (_sp > XB_SPIN_CAP) { atomicAdd(&(bar)[XB_TMO], 1u); break; } } } } while (0)
; __device__ __forceinline__ void xcd_barrier(const XcdBarrier& b) {
;     ...
;             else XB_SPIN(xb_ld(&bar[XB_TOPGEN]) == tg, bar);
;             __builtin_amdgcn_fence(__ATOMIC_ACQUIRE, "agent");
;             xb_add(&bar[XB_XGEN(b.x)], 1u);
;             asm volatile("s_waitcnt vmcnt(0)" ::: "memory");
;             { unsigned inv_probe_; const unsigned* invp_ = bar + XB_TMO; asm volatile("global_load_dword %0, %1, off sc1\n\ts_waitcnt vmcnt(0)" : "=v"(inv_probe_) : "v"(invp_) : "memory"); }
;         } else {
;             XB_SPIN(xb_ld(&bar[XB_XGEN(b.x)]) == gen, bar);
.LBB0_252:
	s_and_b32 s28, s7, 0xff
	s_mov_b64 s[26:27], -1
	s_cmp_lg_u32 s28, 0
	s_mov_b64 s[30:31], -1
	s_nop 0
	s_cbranch_scc1 .LBB0_255
	global_load_dword v2, v0, s[46:47] sc1
	s_waitcnt vmcnt(0)
	v_cmp_eq_u32_e32 vcc, 0, v2
	s_cbranch_vccnz .LBB0_257
	s_mov_b64 s[30:31], 0
	s_mov_b64 s[28:29], -1

; __device__ __forceinline__ unsigned xb_ld(unsigned* p)              { return __hip_atomic_load(p, __ATOMIC_RELAXED, __HIP_MEMORY_SCOPE_AGENT); }
; __device__ __forceinline__ unsigned xb_add(unsigned* p, unsigned v) { return __hip_atomic_fetch_add(p, v, __ATOMIC_RELAXED, __HIP_MEMORY_SCOPE_AGENT); }
; #define XB_SPIN(cond, bar) do { unsigned _sp = 0; while (cond) { __builtin_amdgcn_s_sleep(1); \
;     if ((++_sp & 255u) == 0u) { if (xb_ld(&(bar)[XB_TMO])) break; if (_sp > XB_SPIN_CAP) { atomicAdd(&(bar)[XB_TMO], 1u); break; } } } } while (0)
; __device__ __forceinline__ void xcd_barrier(const XcdBarrier& b) {
;     ...
;             else XB_SPIN(xb_ld(&bar[XB_TOPGEN]) == tg, bar);
;             __builtin_amdgcn_fence(__ATOMIC_ACQUIRE, "agent");
;             xb_add(&bar[XB_XGEN(b.x)], 1u);
;             asm volatile("s_waitcnt vmcnt(0)" ::: "memory");
;             { unsigned inv_probe_; const unsigned* invp_ = bar + XB_TMO; asm volatile("global_load_dword %0, %1, off sc1\n\ts_waitcnt vmcnt(0)" : "=v"(inv_probe_) : "v"(invp_) : "memory"); }
;         } else {
;             XB_SPIN(xb_ld(&bar[XB_XGEN(b.x)]) == gen, bar);
.LBB0_269:
	s_and_b32 s26, s7, 0xff
	s_cmp_lg_u32 s26, 0
	s_mov_b64 s[28:29], -1
	s_nop 0
	s_cbranch_scc1 .LBB0_272
	global_load_dword v1, v0, s[46:47] sc1
	s_waitcnt vmcnt(0)
	v_cmp_eq_u32_e32 vcc, 0, v1
	s_cbranch_vccnz .LBB0_274
	s_mov_b64 s[28:29], 0
	s_mov_b64 s[26:27], -1

; __device__ __forceinline__ unsigned xb_ld(unsigned* p)              { return __hip_atomic_load(p, __ATOMIC_RELAXED, __HIP_MEMORY_SCOPE_AGENT); }
; __device__ __forceinline__ void xcd_barrier_complete(unsigned* bar, unsigned x, unsigned& nloc, unsigned& nx) {
;     ...
;     for (;;) {
;         sum = 0u; cnt = 0u; mine = 0u;
; #pragma unroll
;         for (unsigned j = 0; j < 16; ++j) { const unsigned c = xb_ld(&bar[XB_XCNT(j)]); sum += c; cnt += (c > 0u) ? 1u : 0u; mine = (j == x) ? c : mine; }
;         if (sum == G) break;
;         __builtin_amdgcn_s_sleep(1);
;         if ((++sp & 255u) == 0u) { if (xb_ld(&bar[XB_TMO])) break; if (sp > XB_SPIN_CAP) { atomicAdd(&bar[XB_TMO], 1u); break; } }
;     }
.LBB0_302:
	global_load_dword v15, v16, s[2:3] sc1
	s_waitcnt lgkmcnt(0)
	global_load_dword v0, v16, s[4:5] sc1
	global_load_dword v1, v16, s[8:9] sc1
	global_load_dword v2, v16, s[16:17] sc1
	global_load_dword v3, v16, s[22:23] sc1
	global_load_dword v4, v16, s[24:25] sc1
	global_load_dword v5, v16, s[26:27] sc1
	global_load_dword v6, v16, s[28:29] sc1
	global_load_dword v7, v16, s[30:31] sc1
	global_load_dword v8, v16, s[36:37] sc1
	global_load_dword v9, v16, s[38:39] sc1
	global_load_dword v10, v16, s[48:49] sc1
	global_load_dword v11, v16, s[50:51] sc1
	global_load_dword v12, v16, s[52:53] sc1
	global_load_dword v13, v16, s[54:55] sc1
	global_load_dword v14, v16, s[60:61] sc1
	s_mov_b64 s[62:63], -1
	s_mov_b64 s[64:65], -1
	s_waitcnt vmcnt(14)
	v_add_u32_e32 v17, v0, v15
	s_waitcnt vmcnt(13)
	v_add_u32_e32 v17, v17, v1
	s_waitcnt vmcnt(12)
	v_add_u32_e32 v17, v17, v2
	s_waitcnt vmcnt(11)
	v_add_u32_e32 v17, v17, v3
	s_waitcnt vmcnt(10)
	v_add_u32_e32 v17, v17, v4
	s_waitcnt vmcnt(9)
	v_add_u32_e32 v17, v17, v5
	s_waitcnt vmcnt(8)
	v_add_u32_e32 v17, v17, v6
	s_waitcnt vmcnt(7)
	v_add_u32_e32 v17, v17, v7
	s_waitcnt vmcnt(6)
	v_add_u32_e32 v17, v17, v8
	s_waitcnt vmcnt(5)
	v_add_u32_e32 v17, v17, v9
	s_waitcnt vmcnt(4)
	v_add_u32_e32 v17, v17, v10
	s_waitcnt vmcnt(3)
	v_add_u32_e32 v17, v17, v11
	s_waitcnt vmcnt(2)
	v_add_u32_e32 v17, v17, v12
	s_waitcnt vmcnt(1)
	v_add_u32_e32 v17, v17, v13
	s_waitcnt vmcnt(0)
	v_add_u32_e32 v17, v17, v14
	v_cmp_eq_u32_e32 vcc, s7, v17
	s_cbranch_vccnz .LBB0_301
	s_and_b32 s62, s35, 0xff
	s_cmp_eq_u32 s62, 0
	s_mov_b64 s[62:63], -1
	s_mov_b64 s[66:67], -1
	s_nop 0
	s_cbranch_scc0 .LBB0_306
	global_load_dword v17, v16, s[46:47] sc1
	s_waitcnt vmcnt(0)
	v_cmp_eq_u32_e32 vcc, 0, v17
	s_cbranch_vccnz .LBB0_308
	s_mov_b64 s[66:67], 0

; __device__ __forceinline__ unsigned xb_ld(unsigned* p)              { return __hip_atomic_load(p, __ATOMIC_RELAXED, __HIP_MEMORY_SCOPE_AGENT); }
; __device__ __forceinline__ void xcd_barrier_complete(unsigned* bar, unsigned x, unsigned& nloc, unsigned& nx) {
;     ...
;     for (;;) {
;         sum = 0u; cnt = 0u; mine = 0u;
; #pragma unroll
;         for (unsigned j = 0; j < 16; ++j) { const unsigned c = xb_ld(&bar[XB_XCNT(j)]); sum += c; cnt += (c > 0u) ? 1u : 0u; mine = (j == x) ? c : mine; }
;         if (sum == G) break;
;         __builtin_amdgcn_s_sleep(1);
;         if ((++sp & 255u) == 0u) { if (xb_ld(&bar[XB_TMO])) break; if (sp > XB_SPIN_CAP) { atomicAdd(&bar[XB_TMO], 1u); break; } }
;     }
.LBB0_391:
	global_load_dword v15, v16, s[4:5] sc1
	s_waitcnt lgkmcnt(0)
	global_load_dword v0, v16, s[8:9] sc1
	global_load_dword v1, v16, s[16:17] sc1
	global_load_dword v2, v16, s[18:19] sc1
	global_load_dword v3, v16, s[20:21] sc1
	global_load_dword v4, v16, s[22:23] sc1
	global_load_dword v5, v16, s[24:25] sc1
	global_load_dword v6, v16, s[26:27] sc1
	global_load_dword v7, v16, s[28:29] sc1
	global_load_dword v8, v16, s[30:31] sc1
	global_load_dword v9, v16, s[36:37] sc1
	global_load_dword v10, v16, s[38:39] sc1
	global_load_dword v11, v16, s[48:49] sc1
	global_load_dword v12, v16, s[50:51] sc1
	global_load_dword v13, v16, s[52:53] sc1
	global_load_dword v14, v16, s[54:55] sc1
	s_mov_b64 s[60:61], -1
	s_mov_b64 s[62:63], -1
	s_waitcnt vmcnt(14)
	v_add_u32_e32 v17, v0, v15
	s_waitcnt vmcnt(13)
	v_add_u32_e32 v17, v17, v1
	s_waitcnt vmcnt(12)
	v_add_u32_e32 v17, v17, v2
	s_waitcnt vmcnt(11)
	v_add_u32_e32 v17, v17, v3
	s_waitcnt vmcnt(10)
	v_add_u32_e32 v17, v17, v4
	s_waitcnt vmcnt(9)
	v_add_u32_e32 v17, v17, v5
	s_waitcnt vmcnt(8)
	v_add_u32_e32 v17, v17, v6
	s_waitcnt vmcnt(7)
	v_add_u32_e32 v17, v17, v7
	s_waitcnt vmcnt(6)
	v_add_u32_e32 v17, v17, v8
	s_waitcnt vmcnt(5)
	v_add_u32_e32 v17, v17, v9
	s_waitcnt vmcnt(4)
	v_add_u32_e32 v17, v17, v10
	s_waitcnt vmcnt(3)
	v_add_u32_e32 v17, v17, v11
	s_waitcnt vmcnt(2)
	v_add_u32_e32 v17, v17, v12
	s_waitcnt vmcnt(1)
	v_add_u32_e32 v17, v17, v13
	s_waitcnt vmcnt(0)
	v_add_u32_e32 v17, v17, v14
	v_cmp_eq_u32_e32 vcc, s7, v17
	s_cbranch_vccnz .LBB0_390
	s_and_b32 s60, s35, 0xff
	s_cmp_eq_u32 s60, 0
	s_mov_b64 s[60:61], -1
	s_mov_b64 s[64:65], -1
	s_nop 0
	s_cbranch_scc0 .LBB0_395
	global_load_dword v17, v16, s[46:47] sc1
	s_waitcnt vmcnt(0)
	v_cmp_eq_u32_e32 vcc, 0, v17
	s_cbranch_vccnz .LBB0_397
	s_mov_b64 s[64:65], 0

; __device__ __forceinline__ unsigned xb_ld(unsigned* p)              { return __hip_atomic_load(p, __ATOMIC_RELAXED, __HIP_MEMORY_SCOPE_AGENT); }
; __device__ __forceinline__ unsigned xb_add(unsigned* p, unsigned v) { return __hip_atomic_fetch_add(p, v, __ATOMIC_RELAXED, __HIP_MEMORY_SCOPE_AGENT); }
; #define XB_SPIN(cond, bar) do { unsigned _sp = 0; while (cond) { __builtin_amdgcn_s_sleep(1); \
;     if ((++_sp & 255u) == 0u) { if (xb_ld(&(bar)[XB_TMO])) break; if (_sp > XB_SPIN_CAP) { atomicAdd(&(bar)[XB_TMO], 1u); break; } } } } while (0)
; __device__ __forceinline__ void xcd_barrier(const XcdBarrier& b) {
;     ...
;             else XB_SPIN(xb_ld(&bar[XB_TOPGEN]) == tg, bar);
;             __builtin_amdgcn_fence(__ATOMIC_ACQUIRE, "agent");
;             xb_add(&bar[XB_XGEN(b.x)], 1u);
;             asm volatile("s_waitcnt vmcnt(0)" ::: "memory");
;             { unsigned inv_probe_; const unsigned* invp_ = bar + XB_TMO; asm volatile("global_load_dword %0, %1, off sc1\n\ts_waitcnt vmcnt(0)" : "=v"(inv_probe_) : "v"(invp_) : "memory"); }
;         } else {
;             XB_SPIN(xb_ld(&bar[XB_XGEN(b.x)]) == gen, bar);
.LBB0_409:
	s_and_b32 s26, s7, 0xff
	s_mov_b64 s[24:25], -1
	s_cmp_lg_u32 s26, 0
	s_mov_b64 s[28:29], -1
	s_nop 0
	s_cbranch_scc1 .LBB0_412
	global_load_dword v2, v0, s[46:47] sc1
	s_waitcnt vmcnt(0)
	v_cmp_eq_u32_e32 vcc, 0, v2
	s_cbranch_vccnz .LBB0_414
	s_mov_b64 s[28:29], 0
	s_mov_b64 s[26:27], -1

; __device__ __forceinline__ unsigned xb_ld(unsigned* p)              { return __hip_atomic_load(p, __ATOMIC_RELAXED, __HIP_MEMORY_SCOPE_AGENT); }
; __device__ __forceinline__ unsigned xb_add(unsigned* p, unsigned v) { return __hip_atomic_fetch_add(p, v, __ATOMIC_RELAXED, __HIP_MEMORY_SCOPE_AGENT); }
; #define XB_SPIN(cond, bar) do { unsigned _sp = 0; while (cond) { __builtin_amdgcn_s_sleep(1); \
;     if ((++_sp & 255u) == 0u) { if (xb_ld(&(bar)[XB_TMO])) break; if (_sp > XB_SPIN_CAP) { atomicAdd(&(bar)[XB_TMO], 1u); break; } } } } while (0)
; __device__ __forceinline__ void xcd_barrier(const XcdBarrier& b) {
;     ...
;             else XB_SPIN(xb_ld(&bar[XB_TOPGEN]) == tg, bar);
;             __builtin_amdgcn_fence(__ATOMIC_ACQUIRE, "agent");
;             xb_add(&bar[XB_XGEN(b.x)], 1u);
;             asm volatile("s_waitcnt vmcnt(0)" ::: "memory");
;             { unsigned inv_probe_; const unsigned* invp_ = bar + XB_TMO; asm volatile("global_load_dword %0, %1, off sc1\n\ts_waitcnt vmcnt(0)" : "=v"(inv_probe_) : "v"(invp_) : "memory"); }
;         } else {
;             XB_SPIN(xb_ld(&bar[XB_XGEN(b.x)]) == gen, bar);
.LBB0_426:
	s_and_b32 s24, s7, 0xff
	s_cmp_lg_u32 s24, 0
	s_mov_b64 s[26:27], -1
	s_nop 0
	s_cbranch_scc1 .LBB0_429
	global_load_dword v1, v0, s[46:47] sc1
	s_waitcnt vmcnt(0)
	v_cmp_eq_u32_e32 vcc, 0, v1
	s_cbranch_vccnz .LBB0_431
	s_mov_b64 s[26:27], 0
	s_mov_b64 s[24:25], -1

; __device__ __forceinline__ unsigned xb_ld(unsigned* p)              { return __hip_atomic_load(p, __ATOMIC_RELAXED, __HIP_MEMORY_SCOPE_AGENT); }
; __device__ __forceinline__ void xcd_barrier_complete(unsigned* bar, unsigned x, unsigned& nloc, unsigned& nx) {
;     ...
;     for (;;) {
;         sum = 0u; cnt = 0u; mine = 0u;
; #pragma unroll
;         for (unsigned j = 0; j < 16; ++j) { const unsigned c = xb_ld(&bar[XB_XCNT(j)]); sum += c; cnt += (c > 0u) ? 1u : 0u; mine = (j == x) ? c : mine; }
;         if (sum == G) break;
;         __builtin_amdgcn_s_sleep(1);
;         if ((++sp & 255u) == 0u) { if (xb_ld(&bar[XB_TMO])) break; if (sp > XB_SPIN_CAP) { atomicAdd(&bar[XB_TMO], 1u); break; } }
;     }
.LBB0_515:
	global_load_dword v15, v16, s[4:5] sc1
	s_waitcnt lgkmcnt(0)
	global_load_dword v0, v16, s[6:7] sc1
	global_load_dword v1, v16, s[8:9] sc1
	global_load_dword v2, v16, s[10:11] sc1
	global_load_dword v3, v16, s[12:13] sc1
	global_load_dword v4, v16, s[14:15] sc1
	global_load_dword v5, v16, s[16:17] sc1
	global_load_dword v6, v16, s[18:19] sc1
	global_load_dword v7, v16, s[20:21] sc1
	global_load_dword v8, v16, s[22:23] sc1
	global_load_dword v9, v16, s[24:25] sc1
	global_load_dword v10, v16, s[26:27] sc1
	global_load_dword v11, v16, s[28:29] sc1
	global_load_dword v12, v16, s[30:31] sc1
	global_load_dword v13, v16, s[34:35] sc1
	global_load_dword v14, v16, s[36:37] sc1
	s_mov_b64 s[38:39], -1
	s_mov_b64 s[48:49], -1
	s_waitcnt vmcnt(14)
	v_add_u32_e32 v17, v0, v15
	s_waitcnt vmcnt(13)
	v_add_u32_e32 v17, v17, v1
	s_waitcnt vmcnt(12)
	v_add_u32_e32 v17, v17, v2
	s_waitcnt vmcnt(11)
	v_add_u32_e32 v17, v17, v3
	s_waitcnt vmcnt(10)
	v_add_u32_e32 v17, v17, v4
	s_waitcnt vmcnt(9)
	v_add_u32_e32 v17, v17, v5
	s_waitcnt vmcnt(8)
	v_add_u32_e32 v17, v17, v6
	s_waitcnt vmcnt(7)
	v_add_u32_e32 v17, v17, v7
	s_waitcnt vmcnt(6)
	v_add_u32_e32 v17, v17, v8
	s_waitcnt vmcnt(5)
	v_add_u32_e32 v17, v17, v9
	s_waitcnt vmcnt(4)
	v_add_u32_e32 v17, v17, v10
	s_waitcnt vmcnt(3)
	v_add_u32_e32 v17, v17, v11
	s_waitcnt vmcnt(2)
	v_add_u32_e32 v17, v17, v12
	s_waitcnt vmcnt(1)
	v_add_u32_e32 v17, v17, v13
	s_waitcnt vmcnt(0)
	v_add_u32_e32 v17, v17, v14
	v_cmp_eq_u32_e32 vcc, s52, v17
	s_cbranch_vccnz .LBB0_514
	s_and_b32 s38, s53, 0xff
	s_cmp_eq_u32 s38, 0
	s_mov_b64 s[38:39], -1
	s_mov_b64 s[50:51], -1
	s_nop 0
	s_cbranch_scc0 .LBB0_519
	global_load_dword v17, v16, s[46:47] sc1
	s_waitcnt vmcnt(0)
	v_cmp_eq_u32_e32 vcc, 0, v17
	s_cbranch_vccnz .LBB0_521
	s_mov_b64 s[50:51], 0

; __device__ __forceinline__ unsigned xb_ld(unsigned* p)              { return __hip_atomic_load(p, __ATOMIC_RELAXED, __HIP_MEMORY_SCOPE_AGENT); }
; __device__ __forceinline__ unsigned xb_add(unsigned* p, unsigned v) { return __hip_atomic_fetch_add(p, v, __ATOMIC_RELAXED, __HIP_MEMORY_SCOPE_AGENT); }
; #define XB_SPIN(cond, bar) do { unsigned _sp = 0; while (cond) { __builtin_amdgcn_s_sleep(1); \
;     if ((++_sp & 255u) == 0u) { if (xb_ld(&(bar)[XB_TMO])) break; if (_sp > XB_SPIN_CAP) { atomicAdd(&(bar)[XB_TMO], 1u); break; } } } } while (0)
; __device__ __forceinline__ void xcd_barrier(const XcdBarrier& b) {
;     ...
;             else XB_SPIN(xb_ld(&bar[XB_TOPGEN]) == tg, bar);
;             __builtin_amdgcn_fence(__ATOMIC_ACQUIRE, "agent");
;             xb_add(&bar[XB_XGEN(b.x)], 1u);
;             asm volatile("s_waitcnt vmcnt(0)" ::: "memory");
;             { unsigned inv_probe_; const unsigned* invp_ = bar + XB_TMO; asm volatile("global_load_dword %0, %1, off sc1\n\ts_waitcnt vmcnt(0)" : "=v"(inv_probe_) : "v"(invp_) : "memory"); }
;         } else {
;             XB_SPIN(xb_ld(&bar[XB_XGEN(b.x)]) == gen, bar);
.LBB0_533:
	s_and_b32 s18, s22, 0xff
	s_mov_b64 s[16:17], -1
	s_cmp_lg_u32 s18, 0
	s_mov_b64 s[20:21], -1
	s_nop 0
	s_cbranch_scc1 .LBB0_536
	global_load_dword v2, v0, s[46:47] sc1
	s_waitcnt vmcnt(0)
	v_cmp_eq_u32_e32 vcc, 0, v2
	s_cbranch_vccnz .LBB0_538
	s_mov_b64 s[20:21], 0
	s_mov_b64 s[18:19], -1

; __device__ __forceinline__ unsigned xb_ld(unsigned* p)              { return __hip_atomic_load(p, __ATOMIC_RELAXED, __HIP_MEMORY_SCOPE_AGENT); }
; __device__ __forceinline__ unsigned xb_add(unsigned* p, unsigned v) { return __hip_atomic_fetch_add(p, v, __ATOMIC_RELAXED, __HIP_MEMORY_SCOPE_AGENT); }
; #define XB_SPIN(cond, bar) do { unsigned _sp = 0; while (cond) { __builtin_amdgcn_s_sleep(1); \
;     if ((++_sp & 255u) == 0u) { if (xb_ld(&(bar)[XB_TMO])) break; if (_sp > XB_SPIN_CAP) { atomicAdd(&(bar)[XB_TMO], 1u); break; } } } } while (0)
; __device__ __forceinline__ void xcd_barrier(const XcdBarrier& b) {
;     ...
;             else XB_SPIN(xb_ld(&bar[XB_TOPGEN]) == tg, bar);
;             __builtin_amdgcn_fence(__ATOMIC_ACQUIRE, "agent");
;             xb_add(&bar[XB_XGEN(b.x)], 1u);
;             asm volatile("s_waitcnt vmcnt(0)" ::: "memory");
;             { unsigned inv_probe_; const unsigned* invp_ = bar + XB_TMO; asm volatile("global_load_dword %0, %1, off sc1\n\ts_waitcnt vmcnt(0)" : "=v"(inv_probe_) : "v"(invp_) : "memory"); }
;         } else {
;             XB_SPIN(xb_ld(&bar[XB_XGEN(b.x)]) == gen, bar);
.LBB0_550:
	s_and_b32 s16, s22, 0xff
	s_cmp_lg_u32 s16, 0
	s_mov_b64 s[18:19], -1
	s_nop 0
	s_cbranch_scc1 .LBB0_553
	global_load_dword v1, v0, s[46:47] sc1
	s_waitcnt vmcnt(0)
	v_cmp_eq_u32_e32 vcc, 0, v1
	s_cbranch_vccnz .LBB0_555
	s_mov_b64 s[18:19], 0
	s_mov_b64 s[16:17], -1

; __device__ __forceinline__ unsigned xb_ld(unsigned* p)              { return __hip_atomic_load(p, __ATOMIC_RELAXED, __HIP_MEMORY_SCOPE_AGENT); }
; __device__ __forceinline__ void xcd_barrier_complete(unsigned* bar, unsigned x, unsigned& nloc, unsigned& nx) {
;     ...
;     for (;;) {
;         sum = 0u; cnt = 0u; mine = 0u;
; #pragma unroll
;         for (unsigned j = 0; j < 16; ++j) { const unsigned c = xb_ld(&bar[XB_XCNT(j)]); sum += c; cnt += (c > 0u) ? 1u : 0u; mine = (j == x) ? c : mine; }
;         if (sum == G) break;
;         __builtin_amdgcn_s_sleep(1);
;         if ((++sp & 255u) == 0u) { if (xb_ld(&bar[XB_TMO])) break; if (sp > XB_SPIN_CAP) { atomicAdd(&bar[XB_TMO], 1u); break; } }
;     }
.LBB0_601:
	global_load_dword v15, v16, s[6:7] sc1
	s_waitcnt lgkmcnt(0)
	global_load_dword v0, v16, s[8:9] sc1
	global_load_dword v1, v16, s[10:11] sc1
	global_load_dword v2, v16, s[12:13] sc1
	global_load_dword v3, v16, s[18:19] sc1
	global_load_dword v4, v16, s[20:21] sc1
	global_load_dword v5, v16, s[22:23] sc1
	global_load_dword v6, v16, s[24:25] sc1
	global_load_dword v7, v16, s[26:27] sc1
	global_load_dword v8, v16, s[28:29] sc1
	global_load_dword v9, v16, s[30:31] sc1
	global_load_dword v10, v16, s[34:35] sc1
	global_load_dword v11, v16, s[36:37] sc1
	global_load_dword v12, v16, s[38:39] sc1
	global_load_dword v13, v16, s[48:49] sc1
	global_load_dword v14, v16, s[50:51] sc1
	s_mov_b64 s[52:53], -1
	s_mov_b64 s[54:55], -1
	s_waitcnt vmcnt(14)
	v_add_u32_e32 v17, v0, v15
	s_waitcnt vmcnt(13)
	v_add_u32_e32 v17, v17, v1
	s_waitcnt vmcnt(12)
	v_add_u32_e32 v17, v17, v2
	s_waitcnt vmcnt(11)
	v_add_u32_e32 v17, v17, v3
	s_waitcnt vmcnt(10)
	v_add_u32_e32 v17, v17, v4
	s_waitcnt vmcnt(9)
	v_add_u32_e32 v17, v17, v5
	s_waitcnt vmcnt(8)
	v_add_u32_e32 v17, v17, v6
	s_waitcnt vmcnt(7)
	v_add_u32_e32 v17, v17, v7
	s_waitcnt vmcnt(6)
	v_add_u32_e32 v17, v17, v8
	s_waitcnt vmcnt(5)
	v_add_u32_e32 v17, v17, v9
	s_waitcnt vmcnt(4)
	v_add_u32_e32 v17, v17, v10
	s_waitcnt vmcnt(3)
	v_add_u32_e32 v17, v17, v11
	s_waitcnt vmcnt(2)
	v_add_u32_e32 v17, v17, v12
	s_waitcnt vmcnt(1)
	v_add_u32_e32 v17, v17, v13
	s_waitcnt vmcnt(0)
	v_add_u32_e32 v17, v17, v14
	v_cmp_eq_u32_e32 vcc, s60, v17
	s_cbranch_vccnz .LBB0_600
	s_and_b32 s52, s61, 0xff
	s_cmp_eq_u32 s52, 0
	s_mov_b64 s[52:53], -1
	s_mov_b64 s[58:59], -1
	s_nop 0
	s_cbranch_scc0 .LBB0_605
	global_load_dword v17, v16, s[46:47] sc1
	s_waitcnt vmcnt(0)
	v_cmp_eq_u32_e32 vcc, 0, v17
	s_cbranch_vccnz .LBB0_607
	s_mov_b64 s[58:59], 0

; __device__ __forceinline__ unsigned xb_ld(unsigned* p)              { return __hip_atomic_load(p, __ATOMIC_RELAXED, __HIP_MEMORY_SCOPE_AGENT); }
; __device__ __forceinline__ unsigned xb_add(unsigned* p, unsigned v) { return __hip_atomic_fetch_add(p, v, __ATOMIC_RELAXED, __HIP_MEMORY_SCOPE_AGENT); }
; #define XB_SPIN(cond, bar) do { unsigned _sp = 0; while (cond) { __builtin_amdgcn_s_sleep(1); \
;     if ((++_sp & 255u) == 0u) { if (xb_ld(&(bar)[XB_TMO])) break; if (_sp > XB_SPIN_CAP) { atomicAdd(&(bar)[XB_TMO], 1u); break; } } } } while (0)
; __device__ __forceinline__ void xcd_barrier(const XcdBarrier& b) {
;     ...
;             else XB_SPIN(xb_ld(&bar[XB_TOPGEN]) == tg, bar);
;             __builtin_amdgcn_fence(__ATOMIC_ACQUIRE, "agent");
;             xb_add(&bar[XB_XGEN(b.x)], 1u);
;             asm volatile("s_waitcnt vmcnt(0)" ::: "memory");
;             { unsigned inv_probe_; const unsigned* invp_ = bar + XB_TMO; asm volatile("global_load_dword %0, %1, off sc1\n\ts_waitcnt vmcnt(0)" : "=v"(inv_probe_) : "v"(invp_) : "memory"); }
;         } else {
;             XB_SPIN(xb_ld(&bar[XB_XGEN(b.x)]) == gen, bar);
.LBB0_619:
	s_and_b32 s24, s28, 0xff
	s_mov_b64 s[22:23], -1
	s_cmp_lg_u32 s24, 0
	s_mov_b64 s[26:27], -1
	s_nop 0
	s_cbranch_scc1 .LBB0_622
	global_load_dword v2, v0, s[46:47] sc1
	s_waitcnt vmcnt(0)
	v_cmp_eq_u32_e32 vcc, 0, v2
	s_cbranch_vccnz .LBB0_624
	s_mov_b64 s[26:27], 0
	s_mov_b64 s[24:25], -1

; __device__ __forceinline__ unsigned xb_ld(unsigned* p)              { return __hip_atomic_load(p, __ATOMIC_RELAXED, __HIP_MEMORY_SCOPE_AGENT); }
; __device__ __forceinline__ unsigned xb_add(unsigned* p, unsigned v) { return __hip_atomic_fetch_add(p, v, __ATOMIC_RELAXED, __HIP_MEMORY_SCOPE_AGENT); }
; #define XB_SPIN(cond, bar) do { unsigned _sp = 0; while (cond) { __builtin_amdgcn_s_sleep(1); \
;     if ((++_sp & 255u) == 0u) { if (xb_ld(&(bar)[XB_TMO])) break; if (_sp > XB_SPIN_CAP) { atomicAdd(&(bar)[XB_TMO], 1u); break; } } } } while (0)
; __device__ __forceinline__ void xcd_barrier(const XcdBarrier& b) {
;     ...
;             else XB_SPIN(xb_ld(&bar[XB_TOPGEN]) == tg, bar);
;             __builtin_amdgcn_fence(__ATOMIC_ACQUIRE, "agent");
;             xb_add(&bar[XB_XGEN(b.x)], 1u);
;             asm volatile("s_waitcnt vmcnt(0)" ::: "memory");
;             { unsigned inv_probe_; const unsigned* invp_ = bar + XB_TMO; asm volatile("global_load_dword %0, %1, off sc1\n\ts_waitcnt vmcnt(0)" : "=v"(inv_probe_) : "v"(invp_) : "memory"); }
;         } else {
;             XB_SPIN(xb_ld(&bar[XB_XGEN(b.x)]) == gen, bar);
.LBB0_636:
	s_and_b32 s22, s28, 0xff
	s_cmp_lg_u32 s22, 0
	s_mov_b64 s[24:25], -1
	s_nop 0
	s_cbranch_scc1 .LBB0_639
	global_load_dword v1, v0, s[46:47] sc1
	s_waitcnt vmcnt(0)
	v_cmp_eq_u32_e32 vcc, 0, v1
	s_cbranch_vccnz .LBB0_641
	s_mov_b64 s[24:25], 0
	s_mov_b64 s[22:23], -1

; __device__ __forceinline__ unsigned xb_ld(unsigned* p)              { return __hip_atomic_load(p, __ATOMIC_RELAXED, __HIP_MEMORY_SCOPE_AGENT); }
; __device__ __forceinline__ void xcd_barrier_complete(unsigned* bar, unsigned x, unsigned& nloc, unsigned& nx) {
;     ...
;     for (;;) {
;         sum = 0u; cnt = 0u; mine = 0u;
; #pragma unroll
;         for (unsigned j = 0; j < 16; ++j) { const unsigned c = xb_ld(&bar[XB_XCNT(j)]); sum += c; cnt += (c > 0u) ? 1u : 0u; mine = (j == x) ? c : mine; }
;         if (sum == G) break;
;         __builtin_amdgcn_s_sleep(1);
;         if ((++sp & 255u) == 0u) { if (xb_ld(&bar[XB_TMO])) break; if (sp > XB_SPIN_CAP) { atomicAdd(&bar[XB_TMO], 1u); break; } }
;     }
.LBB0_697:
	global_load_dword v15, v16, s[6:7] sc1
	s_waitcnt lgkmcnt(0)
	global_load_dword v0, v16, s[8:9] sc1
	global_load_dword v1, v16, s[10:11] sc1
	global_load_dword v2, v16, s[12:13] sc1
	global_load_dword v3, v16, s[16:17] sc1
	global_load_dword v4, v16, s[20:21] sc1
	global_load_dword v5, v16, s[22:23] sc1
	global_load_dword v6, v16, s[24:25] sc1
	global_load_dword v7, v16, s[26:27] sc1
	global_load_dword v8, v16, s[28:29] sc1
	global_load_dword v9, v16, s[30:31] sc1
	global_load_dword v10, v16, s[34:35] sc1
	global_load_dword v11, v16, s[36:37] sc1
	global_load_dword v12, v16, s[38:39] sc1
	global_load_dword v13, v16, s[48:49] sc1
	global_load_dword v14, v16, s[50:51] sc1
	s_mov_b64 s[52:53], -1
	s_mov_b64 s[54:55], -1
	s_waitcnt vmcnt(14)
	v_add_u32_e32 v17, v0, v15
	s_waitcnt vmcnt(13)
	v_add_u32_e32 v17, v17, v1
	s_waitcnt vmcnt(12)
	v_add_u32_e32 v17, v17, v2
	s_waitcnt vmcnt(11)
	v_add_u32_e32 v17, v17, v3
	s_waitcnt vmcnt(10)
	v_add_u32_e32 v17, v17, v4
	s_waitcnt vmcnt(9)
	v_add_u32_e32 v17, v17, v5
	s_waitcnt vmcnt(8)
	v_add_u32_e32 v17, v17, v6
	s_waitcnt vmcnt(7)
	v_add_u32_e32 v17, v17, v7
	s_waitcnt vmcnt(6)
	v_add_u32_e32 v17, v17, v8
	s_waitcnt vmcnt(5)
	v_add_u32_e32 v17, v17, v9
	s_waitcnt vmcnt(4)
	v_add_u32_e32 v17, v17, v10
	s_waitcnt vmcnt(3)
	v_add_u32_e32 v17, v17, v11
	s_waitcnt vmcnt(2)
	v_add_u32_e32 v17, v17, v12
	s_waitcnt vmcnt(1)
	v_add_u32_e32 v17, v17, v13
	s_waitcnt vmcnt(0)
	v_add_u32_e32 v17, v17, v14
	v_cmp_eq_u32_e32 vcc, s60, v17
	s_cbranch_vccnz .LBB0_696
	s_and_b32 s52, s61, 0xff
	s_cmp_eq_u32 s52, 0
	s_mov_b64 s[52:53], -1
	s_mov_b64 s[58:59], -1
	s_nop 0
	s_cbranch_scc0 .LBB0_701
	global_load_dword v17, v16, s[46:47] sc1
	s_waitcnt vmcnt(0)
	v_cmp_eq_u32_e32 vcc, 0, v17
	s_cbranch_vccnz .LBB0_703
	s_mov_b64 s[58:59], 0

; __device__ __forceinline__ unsigned xb_ld(unsigned* p)              { return __hip_atomic_load(p, __ATOMIC_RELAXED, __HIP_MEMORY_SCOPE_AGENT); }
; __device__ __forceinline__ void xcd_barrier_complete(unsigned* bar, unsigned x, unsigned& nloc, unsigned& nx) {
;     ...
;     for (;;) {
;         sum = 0u; cnt = 0u; mine = 0u;
; #pragma unroll
;         for (unsigned j = 0; j < 16; ++j) { const unsigned c = xb_ld(&bar[XB_XCNT(j)]); sum += c; cnt += (c > 0u) ? 1u : 0u; mine = (j == x) ? c : mine; }
;         if (sum == G) break;
;         __builtin_amdgcn_s_sleep(1);
;         if ((++sp & 255u) == 0u) { if (xb_ld(&bar[XB_TMO])) break; if (sp > XB_SPIN_CAP) { atomicAdd(&bar[XB_TMO], 1u); break; } }
;     }
.LBB0_765:
	global_load_dword v15, v16, s[4:5] sc1
	s_waitcnt lgkmcnt(0)
	global_load_dword v0, v16, s[6:7] sc1
	global_load_dword v1, v16, s[8:9] sc1
	global_load_dword v2, v16, s[10:11] sc1
	global_load_dword v3, v16, s[12:13] sc1
	global_load_dword v4, v16, s[16:17] sc1
	global_load_dword v5, v16, s[18:19] sc1
	global_load_dword v6, v16, s[20:21] sc1
	global_load_dword v7, v16, s[22:23] sc1
	global_load_dword v8, v16, s[24:25] sc1
	global_load_dword v9, v16, s[26:27] sc1
	global_load_dword v10, v16, s[28:29] sc1
	global_load_dword v11, v16, s[30:31] sc1
	global_load_dword v12, v16, s[34:35] sc1
	global_load_dword v13, v16, s[36:37] sc1
	global_load_dword v14, v16, s[38:39] sc1
	s_mov_b64 s[48:49], -1
	s_mov_b64 s[50:51], -1
	s_waitcnt vmcnt(14)
	v_add_u32_e32 v17, v0, v15
	s_waitcnt vmcnt(13)
	v_add_u32_e32 v17, v17, v1
	s_waitcnt vmcnt(12)
	v_add_u32_e32 v17, v17, v2
	s_waitcnt vmcnt(11)
	v_add_u32_e32 v17, v17, v3
	s_waitcnt vmcnt(10)
	v_add_u32_e32 v17, v17, v4
	s_waitcnt vmcnt(9)
	v_add_u32_e32 v17, v17, v5
	s_waitcnt vmcnt(8)
	v_add_u32_e32 v17, v17, v6
	s_waitcnt vmcnt(7)
	v_add_u32_e32 v17, v17, v7
	s_waitcnt vmcnt(6)
	v_add_u32_e32 v17, v17, v8
	s_waitcnt vmcnt(5)
	v_add_u32_e32 v17, v17, v9
	s_waitcnt vmcnt(4)
	v_add_u32_e32 v17, v17, v10
	s_waitcnt vmcnt(3)
	v_add_u32_e32 v17, v17, v11
	s_waitcnt vmcnt(2)
	v_add_u32_e32 v17, v17, v12
	s_waitcnt vmcnt(1)
	v_add_u32_e32 v17, v17, v13
	s_waitcnt vmcnt(0)
	v_add_u32_e32 v17, v17, v14
	v_cmp_eq_u32_e32 vcc, s54, v17
	s_cbranch_vccnz .LBB0_764
	s_and_b32 s48, s55, 0xff
	s_cmp_eq_u32 s48, 0
	s_mov_b64 s[48:49], -1
	s_mov_b64 s[52:53], -1
	s_nop 0
	s_cbranch_scc0 .LBB0_769
	global_load_dword v17, v16, s[46:47] sc1
	s_waitcnt vmcnt(0)
	v_cmp_eq_u32_e32 vcc, 0, v17
	s_cbranch_vccnz .LBB0_771
	s_mov_b64 s[52:53], 0

; __device__ __forceinline__ unsigned xb_ld(unsigned* p)              { return __hip_atomic_load(p, __ATOMIC_RELAXED, __HIP_MEMORY_SCOPE_AGENT); }
; __device__ __forceinline__ unsigned xb_add(unsigned* p, unsigned v) { return __hip_atomic_fetch_add(p, v, __ATOMIC_RELAXED, __HIP_MEMORY_SCOPE_AGENT); }
; #define XB_SPIN(cond, bar) do { unsigned _sp = 0; while (cond) { __builtin_amdgcn_s_sleep(1); \
;     if ((++_sp & 255u) == 0u) { if (xb_ld(&(bar)[XB_TMO])) break; if (_sp > XB_SPIN_CAP) { atomicAdd(&(bar)[XB_TMO], 1u); break; } } } } while (0)
; __device__ __forceinline__ void xcd_barrier(const XcdBarrier& b) {
;     ...
;             else XB_SPIN(xb_ld(&bar[XB_TOPGEN]) == tg, bar);
;             __builtin_amdgcn_fence(__ATOMIC_ACQUIRE, "agent");
;             xb_add(&bar[XB_XGEN(b.x)], 1u);
;             asm volatile("s_waitcnt vmcnt(0)" ::: "memory");
;             { unsigned inv_probe_; const unsigned* invp_ = bar + XB_TMO; asm volatile("global_load_dword %0, %1, off sc1\n\ts_waitcnt vmcnt(0)" : "=v"(inv_probe_) : "v"(invp_) : "memory"); }
;         } else {
;             XB_SPIN(xb_ld(&bar[XB_XGEN(b.x)]) == gen, bar);
.LBB0_783:
	s_and_b32 s20, s24, 0xff
	s_mov_b64 s[18:19], -1
	s_cmp_lg_u32 s20, 0
	s_mov_b64 s[22:23], -1
	s_nop 0
	s_cbranch_scc1 .LBB0_786
	global_load_dword v2, v0, s[46:47] sc1
	s_waitcnt vmcnt(0)
	v_cmp_eq_u32_e32 vcc, 0, v2
	s_cbranch_vccnz .LBB0_788
	s_mov_b64 s[22:23], 0
	s_mov_b64 s[20:21], -1

; __device__ __forceinline__ unsigned xb_ld(unsigned* p)              { return __hip_atomic_load(p, __ATOMIC_RELAXED, __HIP_MEMORY_SCOPE_AGENT); }
; __device__ __forceinline__ unsigned xb_add(unsigned* p, unsigned v) { return __hip_atomic_fetch_add(p, v, __ATOMIC_RELAXED, __HIP_MEMORY_SCOPE_AGENT); }
; #define XB_SPIN(cond, bar) do { unsigned _sp = 0; while (cond) { __builtin_amdgcn_s_sleep(1); \
;     if ((++_sp & 255u) == 0u) { if (xb_ld(&(bar)[XB_TMO])) break; if (_sp > XB_SPIN_CAP) { atomicAdd(&(bar)[XB_TMO], 1u); break; } } } } while (0)
; __device__ __forceinline__ void xcd_barrier(const XcdBarrier& b) {
;     ...
;             else XB_SPIN(xb_ld(&bar[XB_TOPGEN]) == tg, bar);
;             __builtin_amdgcn_fence(__ATOMIC_ACQUIRE, "agent");
;             xb_add(&bar[XB_XGEN(b.x)], 1u);
;             asm volatile("s_waitcnt vmcnt(0)" ::: "memory");
;             { unsigned inv_probe_; const unsigned* invp_ = bar + XB_TMO; asm volatile("global_load_dword %0, %1, off sc1\n\ts_waitcnt vmcnt(0)" : "=v"(inv_probe_) : "v"(invp_) : "memory"); }
;         } else {
;             XB_SPIN(xb_ld(&bar[XB_XGEN(b.x)]) == gen, bar);
.LBB0_800:
	s_and_b32 s18, s24, 0xff
	s_cmp_lg_u32 s18, 0
	s_mov_b64 s[20:21], -1
	s_nop 0
	s_cbranch_scc1 .LBB0_803
	global_load_dword v1, v0, s[46:47] sc1
	s_waitcnt vmcnt(0)
	v_cmp_eq_u32_e32 vcc, 0, v1
	s_cbranch_vccnz .LBB0_805
	s_mov_b64 s[20:21], 0
	s_mov_b64 s[18:19], -1

; __device__ __forceinline__ unsigned xb_ld(unsigned* p)              { return __hip_atomic_load(p, __ATOMIC_RELAXED, __HIP_MEMORY_SCOPE_AGENT); }
; __device__ __forceinline__ void xcd_barrier_complete(unsigned* bar, unsigned x, unsigned& nloc, unsigned& nx) {
;     ...
;     for (;;) {
;         sum = 0u; cnt = 0u; mine = 0u;
; #pragma unroll
;         for (unsigned j = 0; j < 16; ++j) { const unsigned c = xb_ld(&bar[XB_XCNT(j)]); sum += c; cnt += (c > 0u) ? 1u : 0u; mine = (j == x) ? c : mine; }
;         if (sum == G) break;
;         __builtin_amdgcn_s_sleep(1);
;         if ((++sp & 255u) == 0u) { if (xb_ld(&bar[XB_TMO])) break; if (sp > XB_SPIN_CAP) { atomicAdd(&bar[XB_TMO], 1u); break; } }
;     }
.LBB0_910:
	global_load_dword v15, v16, s[4:5] sc1
	s_waitcnt lgkmcnt(0)
	global_load_dword v0, v16, s[6:7] sc1
	global_load_dword v1, v16, s[8:9] sc1
	global_load_dword v2, v16, s[10:11] sc1
	global_load_dword v3, v16, s[14:15] sc1
	global_load_dword v4, v16, s[16:17] sc1
	global_load_dword v5, v16, s[18:19] sc1
	global_load_dword v6, v16, s[20:21] sc1
	global_load_dword v7, v16, s[22:23] sc1
	global_load_dword v8, v16, s[24:25] sc1
	global_load_dword v9, v16, s[26:27] sc1
	global_load_dword v10, v16, s[28:29] sc1
	global_load_dword v11, v16, s[30:31] sc1
	global_load_dword v12, v16, s[34:35] sc1
	global_load_dword v13, v16, s[36:37] sc1
	global_load_dword v14, v16, s[38:39] sc1
	s_mov_b64 s[48:49], -1
	s_mov_b64 s[50:51], -1
	s_waitcnt vmcnt(14)
	v_add_u32_e32 v17, v0, v15
	s_waitcnt vmcnt(13)
	v_add_u32_e32 v17, v17, v1
	s_waitcnt vmcnt(12)
	v_add_u32_e32 v17, v17, v2
	s_waitcnt vmcnt(11)
	v_add_u32_e32 v17, v17, v3
	s_waitcnt vmcnt(10)
	v_add_u32_e32 v17, v17, v4
	s_waitcnt vmcnt(9)
	v_add_u32_e32 v17, v17, v5
	s_waitcnt vmcnt(8)
	v_add_u32_e32 v17, v17, v6
	s_waitcnt vmcnt(7)
	v_add_u32_e32 v17, v17, v7
	s_waitcnt vmcnt(6)
	v_add_u32_e32 v17, v17, v8
	s_waitcnt vmcnt(5)
	v_add_u32_e32 v17, v17, v9
	s_waitcnt vmcnt(4)
	v_add_u32_e32 v17, v17, v10
	s_waitcnt vmcnt(3)
	v_add_u32_e32 v17, v17, v11
	s_waitcnt vmcnt(2)
	v_add_u32_e32 v17, v17, v12
	s_waitcnt vmcnt(1)
	v_add_u32_e32 v17, v17, v13
	s_waitcnt vmcnt(0)
	v_add_u32_e32 v17, v17, v14
	v_cmp_eq_u32_e32 vcc, s54, v17
	s_cbranch_vccnz .LBB0_909
	s_and_b32 s48, s55, 0xff
	s_cmp_eq_u32 s48, 0
	s_mov_b64 s[48:49], -1
	s_mov_b64 s[52:53], -1
	s_nop 0
	s_cbranch_scc0 .LBB0_914
	global_load_dword v17, v16, s[46:47] sc1
	s_waitcnt vmcnt(0)
	v_cmp_eq_u32_e32 vcc, 0, v17
	s_cbranch_vccnz .LBB0_916
	s_mov_b64 s[52:53], 0

; __device__ __forceinline__ unsigned xb_ld(unsigned* p)              { return __hip_atomic_load(p, __ATOMIC_RELAXED, __HIP_MEMORY_SCOPE_AGENT); }
; __device__ __forceinline__ void xcd_barrier_complete(unsigned* bar, unsigned x, unsigned& nloc, unsigned& nx) {
;     ...
;     for (;;) {
;         sum = 0u; cnt = 0u; mine = 0u;
; #pragma unroll
;         for (unsigned j = 0; j < 16; ++j) { const unsigned c = xb_ld(&bar[XB_XCNT(j)]); sum += c; cnt += (c > 0u) ? 1u : 0u; mine = (j == x) ? c : mine; }
;         if (sum == G) break;
;         __builtin_amdgcn_s_sleep(1);
;         if ((++sp & 255u) == 0u) { if (xb_ld(&bar[XB_TMO])) break; if (sp > XB_SPIN_CAP) { atomicAdd(&bar[XB_TMO], 1u); break; } }
;     }
.LBB0_978:
	global_load_dword v15, v16, s[4:5] sc1
	s_waitcnt lgkmcnt(0)
	global_load_dword v0, v16, s[6:7] sc1
	global_load_dword v1, v16, s[8:9] sc1
	global_load_dword v2, v16, s[10:11] sc1
	global_load_dword v3, v16, s[12:13] sc1
	global_load_dword v4, v16, s[14:15] sc1
	global_load_dword v5, v16, s[16:17] sc1
	global_load_dword v6, v16, s[18:19] sc1
	global_load_dword v7, v16, s[20:21] sc1
	global_load_dword v8, v16, s[22:23] sc1
	global_load_dword v9, v16, s[24:25] sc1
	global_load_dword v10, v16, s[26:27] sc1
	global_load_dword v11, v16, s[28:29] sc1
	global_load_dword v12, v16, s[30:31] sc1
	global_load_dword v13, v16, s[34:35] sc1
	global_load_dword v14, v16, s[36:37] sc1
	s_mov_b64 s[38:39], -1
	s_mov_b64 s[40:41], -1
	s_waitcnt vmcnt(14)
	v_add_u32_e32 v17, v0, v15
	s_waitcnt vmcnt(13)
	v_add_u32_e32 v17, v17, v1
	s_waitcnt vmcnt(12)
	v_add_u32_e32 v17, v17, v2
	s_waitcnt vmcnt(11)
	v_add_u32_e32 v17, v17, v3
	s_waitcnt vmcnt(10)
	v_add_u32_e32 v17, v17, v4
	s_waitcnt vmcnt(9)
	v_add_u32_e32 v17, v17, v5
	s_waitcnt vmcnt(8)
	v_add_u32_e32 v17, v17, v6
	s_waitcnt vmcnt(7)
	v_add_u32_e32 v17, v17, v7
	s_waitcnt vmcnt(6)
	v_add_u32_e32 v17, v17, v8
	s_waitcnt vmcnt(5)
	v_add_u32_e32 v17, v17, v9
	s_waitcnt vmcnt(4)
	v_add_u32_e32 v17, v17, v10
	s_waitcnt vmcnt(3)
	v_add_u32_e32 v17, v17, v11
	s_waitcnt vmcnt(2)
	v_add_u32_e32 v17, v17, v12
	s_waitcnt vmcnt(1)
	v_add_u32_e32 v17, v17, v13
	s_waitcnt vmcnt(0)
	v_add_u32_e32 v17, v17, v14
	v_cmp_eq_u32_e32 vcc, s43, v17
	s_cbranch_vccnz .LBB0_977
	s_and_b32 s38, s50, 0xff
	s_cmp_eq_u32 s38, 0
	s_mov_b64 s[38:39], -1
	s_mov_b64 s[48:49], -1
	s_nop 0
	s_cbranch_scc0 .LBB0_982
	global_load_dword v17, v16, s[46:47] sc1
	s_waitcnt vmcnt(0)
	v_cmp_eq_u32_e32 vcc, 0, v17
	s_cbranch_vccnz .LBB0_984
	s_mov_b64 s[48:49], 0
